# AB/HBR GEMM epilogue: hand-written lean path, next group's gate/partial loads issued before the current group's stores (two register sets, counted vmcnt), SGPR-base addressing
# speedup vs baseline: 1.0033x; 1.0033x over previous
; __device__ __forceinline__ unsigned pk2(float lo, float hi) { const f32x2_t f = {lo, hi}; const bf16x2_t b = __builtin_convertvector(f, bf16x2_t); return __builtin_bit_cast(unsigned, b); }
; __device__ __forceinline__ float lo16(unsigned v) { return __uint_as_float(v << 16); }
; __device__ __forceinline__ float hi16(unsigned v) { return __uint_as_float(v & 0xffff0000u); }
;   __device__ __forceinline__ void operator()(const f32x4 (&acc)[2][2][4][2], const pg8::Unit& u, int wr, int wc, int fr, int fq) const {
;     ...
;     } else if (mode == EM_AB || mode == EM_HBR) {
;       const u16* sg = (const u16*)(ws + O_SG + (size_t)(slice & 1) * SG_BYTES) + (mode == EM_HBR ? 1024 : 0); u16* mg = (u16*)(ws + O_MG) + (size_t)slice * TS * 1024;
; #pragma unroll
;       for (int g8 = 0; g8 < 4; ++g8) {
;         const int ai = g8 >> 1, m0 = (g8 & 1) * 2;
;         u32x4 sv[2][2], pv[2][2];
; #pragma unroll
;         for (int mm = 0; mm < 2; ++mm)
; #pragma unroll
;           for (int bj = 0; bj < 2; ++bj) {
;             const int row = row0 + ai * 128 + (m0 + mm) * 16, c = col0 + bj * 128;
;             sv[mm][bj] = *(const u32x4*)(sg + (size_t)row * 2048 + c);
;             if (mode == EM_HBR) pv[mm][bj] = *(const u32x4*)(mg + (size_t)row * 1024 + c);
;           }
;         __builtin_amdgcn_sched_barrier(0);
; #pragma unroll
;         for (int mm = 0; mm < 2; ++mm)
; #pragma unroll
;           for (int bj = 0; bj < 2; ++bj) {
;             const int m = m0 + mm, row = row0 + ai * 128 + m * 16, c = col0 + bj * 128;
;             const u32x4 sx = sv[mm][bj];
;             const f32x4 a = acc[ai][bj][m][0], b = acc[ai][bj][m][1];
;             float v[8] = {a[0] * lo16(sx.x), a[1] * hi16(sx.x), a[2] * lo16(sx.y), a[3] * hi16(sx.y), b[0] * lo16(sx.z), b[1] * hi16(sx.z), b[2] * lo16(sx.w), b[3] * hi16(sx.w)};
;             if (mode == EM_HBR) { const u32x4 p = pv[mm][bj];
;               v[0] += lo16(p.x); v[1] += hi16(p.x); v[2] += lo16(p.y); v[3] += hi16(p.y); v[4] += lo16(p.z); v[5] += hi16(p.z); v[6] += lo16(p.w); v[7] += hi16(p.w); }
;             u32x4 o; o.x = pk2(v[0], v[1]); o.y = pk2(v[2], v[3]); o.z = pk2(v[4], v[5]); o.w = pk2(v[6], v[7]);
;             *(u32x4*)(mg + (size_t)row * 1024 + c) = o;
;           }
;         __builtin_amdgcn_sched_barrier(0);
;       }
.LBB0_84:
	s_andn2_b64 vcc, exec, s[10:11]
	s_cbranch_vccnz .LBB0_150
	v_lshlrev_b32_e32 v210, 12, v176
	v_lshl_add_u32 v210, v174, 1, v210
	v_lshlrev_b32_e32 v211, 11, v176
	v_lshl_add_u32 v211, v174, 1, v211
	s_mov_b64 s[12:13], s[60:61]
	s_mov_b64 s[10:11], s[4:5]
	s_mov_b64 s[0:1], s[4:5]
	v_readlane_b32 vcc_lo, v254, 39
	v_readlane_b32 vcc_hi, v254, 40
	s_nop 0
	s_or_b32 vcc_lo, vcc_lo, vcc_hi
	s_cmp_eq_u32 vcc_lo, 0
	s_cbranch_scc1 .Labh_ab
.Labh_hbr:
	global_load_dwordx4 v[130:133], v210, s[12:13]
	global_load_dwordx4 v[146:149], v211, s[10:11]
	global_load_dwordx4 v[134:137], v210, s[12:13] offset:256
	global_load_dwordx4 v[150:153], v211, s[10:11] offset:256
	s_add_u32 s12, s12, 0x10000
	s_addc_u32 s13, s13, 0
	s_add_u32 s10, s10, 0x8000
	s_addc_u32 s11, s11, 0
	global_load_dwordx4 v[138:141], v210, s[12:13]
	global_load_dwordx4 v[154:157], v211, s[10:11]
	global_load_dwordx4 v[142:145], v210, s[12:13] offset:256
	global_load_dwordx4 v[158:161], v211, s[10:11] offset:256
	s_add_u32 s12, s12, 0x10000
	s_addc_u32 s13, s13, 0
	s_add_u32 s10, s10, 0x8000
	s_addc_u32 s11, s11, 0
	global_load_dwordx4 v[178:181], v210, s[12:13]
	global_load_dwordx4 v[194:197], v211, s[10:11]
	global_load_dwordx4 v[182:185], v210, s[12:13] offset:256
	global_load_dwordx4 v[198:201], v211, s[10:11] offset:256
	s_add_u32 s12, s12, 0x10000
	s_addc_u32 s13, s13, 0
	s_add_u32 s10, s10, 0x8000
	s_addc_u32 s11, s11, 0
	global_load_dwordx4 v[186:189], v210, s[12:13]
	global_load_dwordx4 v[202:205], v211, s[10:11]
	global_load_dwordx4 v[190:193], v210, s[12:13] offset:256
	global_load_dwordx4 v[206:209], v211, s[10:11] offset:256
	s_add_u32 s12, s12, 0x50000
	s_addc_u32 s13, s13, 0
	s_add_u32 s10, s10, 0x28000
	s_addc_u32 s11, s11, 0
	s_waitcnt vmcnt(8)
	v_lshlrev_b32_e32 v230, 16, v130
	v_and_b32_e32 v231, 0xffff0000, v130
	v_lshlrev_b32_e32 v234, 16, v131
	v_and_b32_e32 v235, 0xffff0000, v131
	v_lshlrev_b32_e32 v238, 16, v132
	v_and_b32_e32 v239, 0xffff0000, v132
	v_lshlrev_b32_e32 v240, 16, v133
	v_and_b32_e32 v241, 0xffff0000, v133
	v_pk_mul_f32 v[244:245], v[126:127], v[230:231]
	v_pk_mul_f32 v[246:247], v[128:129], v[234:235]
	v_pk_mul_f32 v[248:249], v[122:123], v[238:239]
	v_pk_mul_f32 v[250:251], v[124:125], v[240:241]
	v_lshlrev_b32_e32 v230, 16, v146
	v_and_b32_e32 v231, 0xffff0000, v146
	v_lshlrev_b32_e32 v234, 16, v147
	v_and_b32_e32 v235, 0xffff0000, v147
	v_lshlrev_b32_e32 v238, 16, v148
	v_and_b32_e32 v239, 0xffff0000, v148
	v_lshlrev_b32_e32 v240, 16, v149
	v_and_b32_e32 v241, 0xffff0000, v149
	v_pk_add_f32 v[244:245], v[244:245], v[230:231]
	v_pk_add_f32 v[246:247], v[246:247], v[234:235]
	v_pk_add_f32 v[248:249], v[248:249], v[238:239]
	v_pk_add_f32 v[250:251], v[250:251], v[240:241]
	v_cvt_pk_bf16_f32 v244, v244, v245
	v_cvt_pk_bf16_f32 v245, v246, v247
	v_cvt_pk_bf16_f32 v246, v248, v249
	v_cvt_pk_bf16_f32 v247, v250, v251
	global_store_dwordx4 v211, v[244:247], s[0:1]
	v_lshlrev_b32_e32 v230, 16, v134
	v_and_b32_e32 v231, 0xffff0000, v134
	v_lshlrev_b32_e32 v234, 16, v135
	v_and_b32_e32 v235, 0xffff0000, v135
	v_lshlrev_b32_e32 v238, 16, v136
	v_and_b32_e32 v239, 0xffff0000, v136
	v_lshlrev_b32_e32 v240, 16, v137
	v_and_b32_e32 v241, 0xffff0000, v137
	v_pk_mul_f32 v[244:245], v[60:61], v[230:231]
	v_pk_mul_f32 v[246:247], v[62:63], v[234:235]
	v_pk_mul_f32 v[248:249], v[56:57], v[238:239]
	v_pk_mul_f32 v[250:251], v[58:59], v[240:241]
	v_lshlrev_b32_e32 v230, 16, v150
	v_and_b32_e32 v231, 0xffff0000, v150
	v_lshlrev_b32_e32 v234, 16, v151
	v_and_b32_e32 v235, 0xffff0000, v151
	v_lshlrev_b32_e32 v238, 16, v152
	v_and_b32_e32 v239, 0xffff0000, v152
	v_lshlrev_b32_e32 v240, 16, v153
	v_and_b32_e32 v241, 0xffff0000, v153
	v_pk_add_f32 v[244:245], v[244:245], v[230:231]
	v_pk_add_f32 v[246:247], v[246:247], v[234:235]
	v_pk_add_f32 v[248:249], v[248:249], v[238:239]
	v_pk_add_f32 v[250:251], v[250:251], v[240:241]
	v_cvt_pk_bf16_f32 v244, v244, v245
	v_cvt_pk_bf16_f32 v245, v246, v247
	v_cvt_pk_bf16_f32 v246, v248, v249
	v_cvt_pk_bf16_f32 v247, v250, v251
	global_store_dwordx4 v211, v[244:247], s[0:1] offset:256
	s_add_u32 s0, s0, 0x8000
	s_addc_u32 s1, s1, 0
	v_lshlrev_b32_e32 v230, 16, v138
	v_and_b32_e32 v231, 0xffff0000, v138
	v_lshlrev_b32_e32 v234, 16, v139
	v_and_b32_e32 v235, 0xffff0000, v139
	v_lshlrev_b32_e32 v238, 16, v140
	v_and_b32_e32 v239, 0xffff0000, v140
	v_lshlrev_b32_e32 v240, 16, v141
	v_and_b32_e32 v241, 0xffff0000, v141
	v_pk_mul_f32 v[244:245], v[118:119], v[230:231]
	v_pk_mul_f32 v[246:247], v[120:121], v[234:235]
	v_pk_mul_f32 v[248:249], v[114:115], v[238:239]
	v_pk_mul_f32 v[250:251], v[116:117], v[240:241]
	v_lshlrev_b32_e32 v230, 16, v154
	v_and_b32_e32 v231, 0xffff0000, v154
	v_lshlrev_b32_e32 v234, 16, v155
	v_and_b32_e32 v235, 0xffff0000, v155
	v_lshlrev_b32_e32 v238, 16, v156
	v_and_b32_e32 v239, 0xffff0000, v156
	v_lshlrev_b32_e32 v240, 16, v157
	v_and_b32_e32 v241, 0xffff0000, v157
	v_pk_add_f32 v[244:245], v[244:245], v[230:231]
	v_pk_add_f32 v[246:247], v[246:247], v[234:235]
	v_pk_add_f32 v[248:249], v[248:249], v[238:239]
	v_pk_add_f32 v[250:251], v[250:251], v[240:241]
	v_cvt_pk_bf16_f32 v244, v244, v245
	v_cvt_pk_bf16_f32 v245, v246, v247
	v_cvt_pk_bf16_f32 v246, v248, v249
	v_cvt_pk_bf16_f32 v247, v250, v251
	global_store_dwordx4 v211, v[244:247], s[0:1]
	v_lshlrev_b32_e32 v230, 16, v142
	v_and_b32_e32 v231, 0xffff0000, v142
	v_lshlrev_b32_e32 v234, 16, v143
	v_and_b32_e32 v235, 0xffff0000, v143
	v_lshlrev_b32_e32 v238, 16, v144
	v_and_b32_e32 v239, 0xffff0000, v144
	v_lshlrev_b32_e32 v240, 16, v145
	v_and_b32_e32 v241, 0xffff0000, v145
	v_pk_mul_f32 v[244:245], v[52:53], v[230:231]
; __device__ __forceinline__ unsigned pk2(float lo, float hi) { const f32x2_t f = {lo, hi}; const bf16x2_t b = __builtin_convertvector(f, bf16x2_t); return __builtin_bit_cast(unsigned, b); }
; __device__ __forceinline__ float lo16(unsigned v) { return __uint_as_float(v << 16); }
; __device__ __forceinline__ float hi16(unsigned v) { return __uint_as_float(v & 0xffff0000u); }
;   __device__ __forceinline__ void operator()(const f32x4 (&acc)[2][2][4][2], const pg8::Unit& u, int wr, int wc, int fr, int fq) const {
;     ...
;     } else if (mode == EM_AB || mode == EM_HBR) {
;       const u16* sg = (const u16*)(ws + O_SG + (size_t)(slice & 1) * SG_BYTES) + (mode == EM_HBR ? 1024 : 0); u16* mg = (u16*)(ws + O_MG) + (size_t)slice * TS * 1024;
; #pragma unroll
;       for (int g8 = 0; g8 < 4; ++g8) {
;         const int ai = g8 >> 1, m0 = (g8 & 1) * 2;
;         u32x4 sv[2][2], pv[2][2];
; #pragma unroll
;         for (int mm = 0; mm < 2; ++mm)
; #pragma unroll
;           for (int bj = 0; bj < 2; ++bj) {
;             const int row = row0 + ai * 128 + (m0 + mm) * 16, c = col0 + bj * 128;
;             sv[mm][bj] = *(const u32x4*)(sg + (size_t)row * 2048 + c);
;             if (mode == EM_HBR) pv[mm][bj] = *(const u32x4*)(mg + (size_t)row * 1024 + c);
;           }
;         __builtin_amdgcn_sched_barrier(0);
; #pragma unroll
;         for (int mm = 0; mm < 2; ++mm)
; #pragma unroll
;           for (int bj = 0; bj < 2; ++bj) {
;             const int m = m0 + mm, row = row0 + ai * 128 + m * 16, c = col0 + bj * 128;
;             const u32x4 sx = sv[mm][bj];
;             const f32x4 a = acc[ai][bj][m][0], b = acc[ai][bj][m][1];
;             float v[8] = {a[0] * lo16(sx.x), a[1] * hi16(sx.x), a[2] * lo16(sx.y), a[3] * hi16(sx.y), b[0] * lo16(sx.z), b[1] * hi16(sx.z), b[2] * lo16(sx.w), b[3] * hi16(sx.w)};
;             if (mode == EM_HBR) { const u32x4 p = pv[mm][bj];
;               v[0] += lo16(p.x); v[1] += hi16(p.x); v[2] += lo16(p.y); v[3] += hi16(p.y); v[4] += lo16(p.z); v[5] += hi16(p.z); v[6] += lo16(p.w); v[7] += hi16(p.w); }
;             u32x4 o; o.x = pk2(v[0], v[1]); o.y = pk2(v[2], v[3]); o.z = pk2(v[4], v[5]); o.w = pk2(v[6], v[7]);
;             *(u32x4*)(mg + (size_t)row * 1024 + c) = o;
;           }
;         __builtin_amdgcn_sched_barrier(0);
;       }
	v_pk_mul_f32 v[246:247], v[54:55], v[234:235]
	v_pk_mul_f32 v[248:249], v[48:49], v[238:239]
	v_pk_mul_f32 v[250:251], v[50:51], v[240:241]
	v_lshlrev_b32_e32 v230, 16, v158
	v_and_b32_e32 v231, 0xffff0000, v158
	v_lshlrev_b32_e32 v234, 16, v159
	v_and_b32_e32 v235, 0xffff0000, v159
	v_lshlrev_b32_e32 v238, 16, v160
	v_and_b32_e32 v239, 0xffff0000, v160
	v_lshlrev_b32_e32 v240, 16, v161
	v_and_b32_e32 v241, 0xffff0000, v161
	v_pk_add_f32 v[244:245], v[244:245], v[230:231]
	v_pk_add_f32 v[246:247], v[246:247], v[234:235]
	v_pk_add_f32 v[248:249], v[248:249], v[238:239]
	v_pk_add_f32 v[250:251], v[250:251], v[240:241]
	v_cvt_pk_bf16_f32 v244, v244, v245
	v_cvt_pk_bf16_f32 v245, v246, v247
	v_cvt_pk_bf16_f32 v246, v248, v249
	v_cvt_pk_bf16_f32 v247, v250, v251
	global_store_dwordx4 v211, v[244:247], s[0:1] offset:256
	s_add_u32 s0, s0, 0x8000
	s_addc_u32 s1, s1, 0
	global_load_dwordx4 v[130:133], v210, s[12:13]
	global_load_dwordx4 v[146:149], v211, s[10:11]
	global_load_dwordx4 v[134:137], v210, s[12:13] offset:256
	global_load_dwordx4 v[150:153], v211, s[10:11] offset:256
	s_add_u32 s12, s12, 0x10000
	s_addc_u32 s13, s13, 0
	s_add_u32 s10, s10, 0x8000
	s_addc_u32 s11, s11, 0
	global_load_dwordx4 v[138:141], v210, s[12:13]
	global_load_dwordx4 v[154:157], v211, s[10:11]
	global_load_dwordx4 v[142:145], v210, s[12:13] offset:256
	global_load_dwordx4 v[158:161], v211, s[10:11] offset:256
	s_add_u32 s12, s12, 0x10000
	s_addc_u32 s13, s13, 0
	s_add_u32 s10, s10, 0x8000
	s_addc_u32 s11, s11, 0
	s_waitcnt vmcnt(12)
	v_lshlrev_b32_e32 v230, 16, v178
	v_and_b32_e32 v231, 0xffff0000, v178
	v_lshlrev_b32_e32 v234, 16, v179
	v_and_b32_e32 v235, 0xffff0000, v179
	v_lshlrev_b32_e32 v238, 16, v180
	v_and_b32_e32 v239, 0xffff0000, v180
	v_lshlrev_b32_e32 v240, 16, v181
	v_and_b32_e32 v241, 0xffff0000, v181
	v_pk_mul_f32 v[244:245], v[110:111], v[230:231]
	v_pk_mul_f32 v[246:247], v[112:113], v[234:235]
	v_pk_mul_f32 v[248:249], v[106:107], v[238:239]
	v_pk_mul_f32 v[250:251], v[108:109], v[240:241]
	v_lshlrev_b32_e32 v230, 16, v194
	v_and_b32_e32 v231, 0xffff0000, v194
	v_lshlrev_b32_e32 v234, 16, v195
	v_and_b32_e32 v235, 0xffff0000, v195
	v_lshlrev_b32_e32 v238, 16, v196
	v_and_b32_e32 v239, 0xffff0000, v196
	v_lshlrev_b32_e32 v240, 16, v197
	v_and_b32_e32 v241, 0xffff0000, v197
	v_pk_add_f32 v[244:245], v[244:245], v[230:231]
	v_pk_add_f32 v[246:247], v[246:247], v[234:235]
	v_pk_add_f32 v[248:249], v[248:249], v[238:239]
	v_pk_add_f32 v[250:251], v[250:251], v[240:241]
	v_cvt_pk_bf16_f32 v244, v244, v245
	v_cvt_pk_bf16_f32 v245, v246, v247
	v_cvt_pk_bf16_f32 v246, v248, v249
	v_cvt_pk_bf16_f32 v247, v250, v251
	global_store_dwordx4 v211, v[244:247], s[0:1]
	v_lshlrev_b32_e32 v230, 16, v182
	v_and_b32_e32 v231, 0xffff0000, v182
	v_lshlrev_b32_e32 v234, 16, v183
	v_and_b32_e32 v235, 0xffff0000, v183
	v_lshlrev_b32_e32 v238, 16, v184
	v_and_b32_e32 v239, 0xffff0000, v184
	v_lshlrev_b32_e32 v240, 16, v185
	v_and_b32_e32 v241, 0xffff0000, v185
	v_pk_mul_f32 v[244:245], v[44:45], v[230:231]
	v_pk_mul_f32 v[246:247], v[46:47], v[234:235]
	v_pk_mul_f32 v[248:249], v[40:41], v[238:239]
	v_pk_mul_f32 v[250:251], v[42:43], v[240:241]
	v_lshlrev_b32_e32 v230, 16, v198
	v_and_b32_e32 v231, 0xffff0000, v198
	v_lshlrev_b32_e32 v234, 16, v199
	v_and_b32_e32 v235, 0xffff0000, v199
	v_lshlrev_b32_e32 v238, 16, v200
	v_and_b32_e32 v239, 0xffff0000, v200
	v_lshlrev_b32_e32 v240, 16, v201
	v_and_b32_e32 v241, 0xffff0000, v201
	v_pk_add_f32 v[244:245], v[244:245], v[230:231]
	v_pk_add_f32 v[246:247], v[246:247], v[234:235]
	v_pk_add_f32 v[248:249], v[248:249], v[238:239]
	v_pk_add_f32 v[250:251], v[250:251], v[240:241]
	v_cvt_pk_bf16_f32 v244, v244, v245
	v_cvt_pk_bf16_f32 v245, v246, v247
	v_cvt_pk_bf16_f32 v246, v248, v249
	v_cvt_pk_bf16_f32 v247, v250, v251
	global_store_dwordx4 v211, v[244:247], s[0:1] offset:256
	s_add_u32 s0, s0, 0x8000
	s_addc_u32 s1, s1, 0
	v_lshlrev_b32_e32 v230, 16, v186
	v_and_b32_e32 v231, 0xffff0000, v186
	v_lshlrev_b32_e32 v234, 16, v187
	v_and_b32_e32 v235, 0xffff0000, v187
	v_lshlrev_b32_e32 v238, 16, v188
	v_and_b32_e32 v239, 0xffff0000, v188
	v_lshlrev_b32_e32 v240, 16, v189
	v_and_b32_e32 v241, 0xffff0000, v189
	v_pk_mul_f32 v[244:245], v[102:103], v[230:231]
	v_pk_mul_f32 v[246:247], v[104:105], v[234:235]
	v_pk_mul_f32 v[248:249], v[98:99], v[238:239]
	v_pk_mul_f32 v[250:251], v[100:101], v[240:241]
	v_lshlrev_b32_e32 v230, 16, v202
	v_and_b32_e32 v231, 0xffff0000, v202
	v_lshlrev_b32_e32 v234, 16, v203
	v_and_b32_e32 v235, 0xffff0000, v203
	v_lshlrev_b32_e32 v238, 16, v204
	v_and_b32_e32 v239, 0xffff0000, v204
	v_lshlrev_b32_e32 v240, 16, v205
	v_and_b32_e32 v241, 0xffff0000, v205
	v_pk_add_f32 v[244:245], v[244:245], v[230:231]
	v_pk_add_f32 v[246:247], v[246:247], v[234:235]
	v_pk_add_f32 v[248:249], v[248:249], v[238:239]
	v_pk_add_f32 v[250:251], v[250:251], v[240:241]
	v_cvt_pk_bf16_f32 v244, v244, v245
	v_cvt_pk_bf16_f32 v245, v246, v247
	v_cvt_pk_bf16_f32 v246, v248, v249
	v_cvt_pk_bf16_f32 v247, v250, v251
	global_store_dwordx4 v211, v[244:247], s[0:1]
	v_lshlrev_b32_e32 v230, 16, v190
	v_and_b32_e32 v231, 0xffff0000, v190
	v_lshlrev_b32_e32 v234, 16, v191
	v_and_b32_e32 v235, 0xffff0000, v191
	v_lshlrev_b32_e32 v238, 16, v192
	v_and_b32_e32 v239, 0xffff0000, v192
	v_lshlrev_b32_e32 v240, 16, v193
	v_and_b32_e32 v241, 0xffff0000, v193
	v_pk_mul_f32 v[244:245], v[36:37], v[230:231]
	v_pk_mul_f32 v[246:247], v[38:39], v[234:235]
	v_pk_mul_f32 v[248:249], v[32:33], v[238:239]
	v_pk_mul_f32 v[250:251], v[34:35], v[240:241]
	v_lshlrev_b32_e32 v230, 16, v206
	v_and_b32_e32 v231, 0xffff0000, v206
	v_lshlrev_b32_e32 v234, 16, v207
	v_and_b32_e32 v235, 0xffff0000, v207
	v_lshlrev_b32_e32 v238, 16, v208
	v_and_b32_e32 v239, 0xffff0000, v208
	v_lshlrev_b32_e32 v240, 16, v209
	v_and_b32_e32 v241, 0xffff0000, v209
	v_pk_add_f32 v[244:245], v[244:245], v[230:231]
	v_pk_add_f32 v[246:247], v[246:247], v[234:235]
	v_pk_add_f32 v[248:249], v[248:249], v[238:239]
	v_pk_add_f32 v[250:251], v[250:251], v[240:241]
	v_cvt_pk_bf16_f32 v244, v244, v245
	v_cvt_pk_bf16_f32 v245, v246, v247
	v_cvt_pk_bf16_f32 v246, v248, v249
	v_cvt_pk_bf16_f32 v247, v250, v251
	global_store_dwordx4 v211, v[244:247], s[0:1] offset:256
	s_add_u32 s0, s0, 0x28000
	s_addc_u32 s1, s1, 0
	global_load_dwordx4 v[178:181], v210, s[12:13]
	global_load_dwordx4 v[194:197], v211, s[10:11]
	global_load_dwordx4 v[182:185], v210, s[12:13] offset:256
	global_load_dwordx4 v[198:201], v211, s[10:11] offset:256
	s_add_u32 s12, s12, 0x10000
	s_addc_u32 s13, s13, 0
	s_add_u32 s10, s10, 0x8000
	s_addc_u32 s11, s11, 0
	global_load_dwordx4 v[186:189], v210, s[12:13]
	global_load_dwordx4 v[202:205], v211, s[10:11]
	global_load_dwordx4 v[190:193], v210, s[12:13] offset:256
	global_load_dwordx4 v[206:209], v211, s[10:11] offset:256
	s_waitcnt vmcnt(12)
; __device__ __forceinline__ unsigned pk2(float lo, float hi) { const f32x2_t f = {lo, hi}; const bf16x2_t b = __builtin_convertvector(f, bf16x2_t); return __builtin_bit_cast(unsigned, b); }
; __device__ __forceinline__ float lo16(unsigned v) { return __uint_as_float(v << 16); }
; __device__ __forceinline__ float hi16(unsigned v) { return __uint_as_float(v & 0xffff0000u); }
;   __device__ __forceinline__ void operator()(const f32x4 (&acc)[2][2][4][2], const pg8::Unit& u, int wr, int wc, int fr, int fq) const {
;     ...
;     } else if (mode == EM_AB || mode == EM_HBR) {
;       const u16* sg = (const u16*)(ws + O_SG + (size_t)(slice & 1) * SG_BYTES) + (mode == EM_HBR ? 1024 : 0); u16* mg = (u16*)(ws + O_MG) + (size_t)slice * TS * 1024;
; #pragma unroll
;       for (int g8 = 0; g8 < 4; ++g8) {
;         const int ai = g8 >> 1, m0 = (g8 & 1) * 2;
;         u32x4 sv[2][2], pv[2][2];
; #pragma unroll
;         for (int mm = 0; mm < 2; ++mm)
; #pragma unroll
;           for (int bj = 0; bj < 2; ++bj) {
;             const int row = row0 + ai * 128 + (m0 + mm) * 16, c = col0 + bj * 128;
;             sv[mm][bj] = *(const u32x4*)(sg + (size_t)row * 2048 + c);
;             if (mode == EM_HBR) pv[mm][bj] = *(const u32x4*)(mg + (size_t)row * 1024 + c);
;           }
;         __builtin_amdgcn_sched_barrier(0);
; #pragma unroll
;         for (int mm = 0; mm < 2; ++mm)
; #pragma unroll
;           for (int bj = 0; bj < 2; ++bj) {
;             const int m = m0 + mm, row = row0 + ai * 128 + m * 16, c = col0 + bj * 128;
;             const u32x4 sx = sv[mm][bj];
;             const f32x4 a = acc[ai][bj][m][0], b = acc[ai][bj][m][1];
;             float v[8] = {a[0] * lo16(sx.x), a[1] * hi16(sx.x), a[2] * lo16(sx.y), a[3] * hi16(sx.y), b[0] * lo16(sx.z), b[1] * hi16(sx.z), b[2] * lo16(sx.w), b[3] * hi16(sx.w)};
;             if (mode == EM_HBR) { const u32x4 p = pv[mm][bj];
;               v[0] += lo16(p.x); v[1] += hi16(p.x); v[2] += lo16(p.y); v[3] += hi16(p.y); v[4] += lo16(p.z); v[5] += hi16(p.z); v[6] += lo16(p.w); v[7] += hi16(p.w); }
;             u32x4 o; o.x = pk2(v[0], v[1]); o.y = pk2(v[2], v[3]); o.z = pk2(v[4], v[5]); o.w = pk2(v[6], v[7]);
;             *(u32x4*)(mg + (size_t)row * 1024 + c) = o;
;           }
;         __builtin_amdgcn_sched_barrier(0);
;       }
	v_lshlrev_b32_e32 v230, 16, v130
	v_and_b32_e32 v231, 0xffff0000, v130
	v_lshlrev_b32_e32 v234, 16, v131
	v_and_b32_e32 v235, 0xffff0000, v131
	v_lshlrev_b32_e32 v238, 16, v132
	v_and_b32_e32 v239, 0xffff0000, v132
	v_lshlrev_b32_e32 v240, 16, v133
	v_and_b32_e32 v241, 0xffff0000, v133
	v_pk_mul_f32 v[244:245], v[94:95], v[230:231]
	v_pk_mul_f32 v[246:247], v[96:97], v[234:235]
	v_pk_mul_f32 v[248:249], v[90:91], v[238:239]
	v_pk_mul_f32 v[250:251], v[92:93], v[240:241]
	v_lshlrev_b32_e32 v230, 16, v146
	v_and_b32_e32 v231, 0xffff0000, v146
	v_lshlrev_b32_e32 v234, 16, v147
	v_and_b32_e32 v235, 0xffff0000, v147
	v_lshlrev_b32_e32 v238, 16, v148
	v_and_b32_e32 v239, 0xffff0000, v148
	v_lshlrev_b32_e32 v240, 16, v149
	v_and_b32_e32 v241, 0xffff0000, v149
	v_pk_add_f32 v[244:245], v[244:245], v[230:231]
	v_pk_add_f32 v[246:247], v[246:247], v[234:235]
	v_pk_add_f32 v[248:249], v[248:249], v[238:239]
	v_pk_add_f32 v[250:251], v[250:251], v[240:241]
	v_cvt_pk_bf16_f32 v244, v244, v245
	v_cvt_pk_bf16_f32 v245, v246, v247
	v_cvt_pk_bf16_f32 v246, v248, v249
	v_cvt_pk_bf16_f32 v247, v250, v251
	global_store_dwordx4 v211, v[244:247], s[0:1]
	v_lshlrev_b32_e32 v230, 16, v134
	v_and_b32_e32 v231, 0xffff0000, v134
	v_lshlrev_b32_e32 v234, 16, v135
	v_and_b32_e32 v235, 0xffff0000, v135
	v_lshlrev_b32_e32 v238, 16, v136
	v_and_b32_e32 v239, 0xffff0000, v136
	v_lshlrev_b32_e32 v240, 16, v137
	v_and_b32_e32 v241, 0xffff0000, v137
	v_pk_mul_f32 v[244:245], v[28:29], v[230:231]
	v_pk_mul_f32 v[246:247], v[30:31], v[234:235]
	v_pk_mul_f32 v[248:249], v[24:25], v[238:239]
	v_pk_mul_f32 v[250:251], v[26:27], v[240:241]
	v_lshlrev_b32_e32 v230, 16, v150
	v_and_b32_e32 v231, 0xffff0000, v150
	v_lshlrev_b32_e32 v234, 16, v151
	v_and_b32_e32 v235, 0xffff0000, v151
	v_lshlrev_b32_e32 v238, 16, v152
	v_and_b32_e32 v239, 0xffff0000, v152
	v_lshlrev_b32_e32 v240, 16, v153
	v_and_b32_e32 v241, 0xffff0000, v153
	v_pk_add_f32 v[244:245], v[244:245], v[230:231]
	v_pk_add_f32 v[246:247], v[246:247], v[234:235]
	v_pk_add_f32 v[248:249], v[248:249], v[238:239]
	v_pk_add_f32 v[250:251], v[250:251], v[240:241]
	v_cvt_pk_bf16_f32 v244, v244, v245
	v_cvt_pk_bf16_f32 v245, v246, v247
	v_cvt_pk_bf16_f32 v246, v248, v249
	v_cvt_pk_bf16_f32 v247, v250, v251
	global_store_dwordx4 v211, v[244:247], s[0:1] offset:256
	s_add_u32 s0, s0, 0x8000
	s_addc_u32 s1, s1, 0
	v_lshlrev_b32_e32 v230, 16, v138
	v_and_b32_e32 v231, 0xffff0000, v138
	v_lshlrev_b32_e32 v234, 16, v139
	v_and_b32_e32 v235, 0xffff0000, v139
	v_lshlrev_b32_e32 v238, 16, v140
	v_and_b32_e32 v239, 0xffff0000, v140
	v_lshlrev_b32_e32 v240, 16, v141
	v_and_b32_e32 v241, 0xffff0000, v141
	v_pk_mul_f32 v[244:245], v[86:87], v[230:231]
	v_pk_mul_f32 v[246:247], v[88:89], v[234:235]
	v_pk_mul_f32 v[248:249], v[82:83], v[238:239]
	v_pk_mul_f32 v[250:251], v[84:85], v[240:241]
	v_lshlrev_b32_e32 v230, 16, v154
	v_and_b32_e32 v231, 0xffff0000, v154
	v_lshlrev_b32_e32 v234, 16, v155
	v_and_b32_e32 v235, 0xffff0000, v155
	v_lshlrev_b32_e32 v238, 16, v156
	v_and_b32_e32 v239, 0xffff0000, v156
	v_lshlrev_b32_e32 v240, 16, v157
	v_and_b32_e32 v241, 0xffff0000, v157
	v_pk_add_f32 v[244:245], v[244:245], v[230:231]
	v_pk_add_f32 v[246:247], v[246:247], v[234:235]
	v_pk_add_f32 v[248:249], v[248:249], v[238:239]
	v_pk_add_f32 v[250:251], v[250:251], v[240:241]
	v_cvt_pk_bf16_f32 v244, v244, v245
	v_cvt_pk_bf16_f32 v245, v246, v247
	v_cvt_pk_bf16_f32 v246, v248, v249
	v_cvt_pk_bf16_f32 v247, v250, v251
	global_store_dwordx4 v211, v[244:247], s[0:1]
	v_lshlrev_b32_e32 v230, 16, v142
	v_and_b32_e32 v231, 0xffff0000, v142
	v_lshlrev_b32_e32 v234, 16, v143
	v_and_b32_e32 v235, 0xffff0000, v143
	v_lshlrev_b32_e32 v238, 16, v144
	v_and_b32_e32 v239, 0xffff0000, v144
	v_lshlrev_b32_e32 v240, 16, v145
	v_and_b32_e32 v241, 0xffff0000, v145
	v_pk_mul_f32 v[244:245], v[20:21], v[230:231]
	v_pk_mul_f32 v[246:247], v[22:23], v[234:235]
	v_pk_mul_f32 v[248:249], v[16:17], v[238:239]
	v_pk_mul_f32 v[250:251], v[18:19], v[240:241]
	v_lshlrev_b32_e32 v230, 16, v158
	v_and_b32_e32 v231, 0xffff0000, v158
	v_lshlrev_b32_e32 v234, 16, v159
	v_and_b32_e32 v235, 0xffff0000, v159
	v_lshlrev_b32_e32 v238, 16, v160
	v_and_b32_e32 v239, 0xffff0000, v160
	v_lshlrev_b32_e32 v240, 16, v161
	v_and_b32_e32 v241, 0xffff0000, v161
	v_pk_add_f32 v[244:245], v[244:245], v[230:231]
	v_pk_add_f32 v[246:247], v[246:247], v[234:235]
	v_pk_add_f32 v[248:249], v[248:249], v[238:239]
	v_pk_add_f32 v[250:251], v[250:251], v[240:241]
	v_cvt_pk_bf16_f32 v244, v244, v245
	v_cvt_pk_bf16_f32 v245, v246, v247
	v_cvt_pk_bf16_f32 v246, v248, v249
	v_cvt_pk_bf16_f32 v247, v250, v251
	global_store_dwordx4 v211, v[244:247], s[0:1] offset:256
	s_add_u32 s0, s0, 0x8000
	s_addc_u32 s1, s1, 0
	s_waitcnt vmcnt(4)
; __device__ __forceinline__ unsigned pk2(float lo, float hi) { const f32x2_t f = {lo, hi}; const bf16x2_t b = __builtin_convertvector(f, bf16x2_t); return __builtin_bit_cast(unsigned, b); }
; __device__ __forceinline__ float lo16(unsigned v) { return __uint_as_float(v << 16); }
; __device__ __forceinline__ float hi16(unsigned v) { return __uint_as_float(v & 0xffff0000u); }
;   __device__ __forceinline__ void operator()(const f32x4 (&acc)[2][2][4][2], const pg8::Unit& u, int wr, int wc, int fr, int fq) const {
;     ...
;     } else if (mode == EM_AB || mode == EM_HBR) {
;       const u16* sg = (const u16*)(ws + O_SG + (size_t)(slice & 1) * SG_BYTES) + (mode == EM_HBR ? 1024 : 0); u16* mg = (u16*)(ws + O_MG) + (size_t)slice * TS * 1024;
; #pragma unroll
;       for (int g8 = 0; g8 < 4; ++g8) {
;         const int ai = g8 >> 1, m0 = (g8 & 1) * 2;
;         u32x4 sv[2][2], pv[2][2];
; #pragma unroll
;         for (int mm = 0; mm < 2; ++mm)
; #pragma unroll
;           for (int bj = 0; bj < 2; ++bj) {
;             const int row = row0 + ai * 128 + (m0 + mm) * 16, c = col0 + bj * 128;
;             sv[mm][bj] = *(const u32x4*)(sg + (size_t)row * 2048 + c);
;             if (mode == EM_HBR) pv[mm][bj] = *(const u32x4*)(mg + (size_t)row * 1024 + c);
;           }
;         __builtin_amdgcn_sched_barrier(0);
; #pragma unroll
;         for (int mm = 0; mm < 2; ++mm)
; #pragma unroll
;           for (int bj = 0; bj < 2; ++bj) {
;             const int m = m0 + mm, row = row0 + ai * 128 + m * 16, c = col0 + bj * 128;
;             const u32x4 sx = sv[mm][bj];
;             const f32x4 a = acc[ai][bj][m][0], b = acc[ai][bj][m][1];
;             float v[8] = {a[0] * lo16(sx.x), a[1] * hi16(sx.x), a[2] * lo16(sx.y), a[3] * hi16(sx.y), b[0] * lo16(sx.z), b[1] * hi16(sx.z), b[2] * lo16(sx.w), b[3] * hi16(sx.w)};
;             if (mode == EM_HBR) { const u32x4 p = pv[mm][bj];
;               v[0] += lo16(p.x); v[1] += hi16(p.x); v[2] += lo16(p.y); v[3] += hi16(p.y); v[4] += lo16(p.z); v[5] += hi16(p.z); v[6] += lo16(p.w); v[7] += hi16(p.w); }
;             u32x4 o; o.x = pk2(v[0], v[1]); o.y = pk2(v[2], v[3]); o.z = pk2(v[4], v[5]); o.w = pk2(v[6], v[7]);
;             *(u32x4*)(mg + (size_t)row * 1024 + c) = o;
;           }
;         __builtin_amdgcn_sched_barrier(0);
;       }
	v_lshlrev_b32_e32 v230, 16, v178
	v_and_b32_e32 v231, 0xffff0000, v178
	v_lshlrev_b32_e32 v234, 16, v179
	v_and_b32_e32 v235, 0xffff0000, v179
	v_lshlrev_b32_e32 v238, 16, v180
	v_and_b32_e32 v239, 0xffff0000, v180
	v_lshlrev_b32_e32 v240, 16, v181
	v_and_b32_e32 v241, 0xffff0000, v181
	v_pk_mul_f32 v[244:245], v[76:77], v[230:231]
	v_pk_mul_f32 v[246:247], v[78:79], v[234:235]
	v_pk_mul_f32 v[248:249], v[72:73], v[238:239]
	v_pk_mul_f32 v[250:251], v[74:75], v[240:241]
	v_lshlrev_b32_e32 v230, 16, v194
	v_and_b32_e32 v231, 0xffff0000, v194
	v_lshlrev_b32_e32 v234, 16, v195
	v_and_b32_e32 v235, 0xffff0000, v195
	v_lshlrev_b32_e32 v238, 16, v196
	v_and_b32_e32 v239, 0xffff0000, v196
	v_lshlrev_b32_e32 v240, 16, v197
	v_and_b32_e32 v241, 0xffff0000, v197
	v_pk_add_f32 v[244:245], v[244:245], v[230:231]
	v_pk_add_f32 v[246:247], v[246:247], v[234:235]
	v_pk_add_f32 v[248:249], v[248:249], v[238:239]
	v_pk_add_f32 v[250:251], v[250:251], v[240:241]
	v_cvt_pk_bf16_f32 v244, v244, v245
	v_cvt_pk_bf16_f32 v245, v246, v247
	v_cvt_pk_bf16_f32 v246, v248, v249
	v_cvt_pk_bf16_f32 v247, v250, v251
	global_store_dwordx4 v211, v[244:247], s[0:1]
	v_lshlrev_b32_e32 v230, 16, v182
	v_and_b32_e32 v231, 0xffff0000, v182
	v_lshlrev_b32_e32 v234, 16, v183
	v_and_b32_e32 v235, 0xffff0000, v183
	v_lshlrev_b32_e32 v238, 16, v184
	v_and_b32_e32 v239, 0xffff0000, v184
	v_lshlrev_b32_e32 v240, 16, v185
	v_and_b32_e32 v241, 0xffff0000, v185
	v_pk_mul_f32 v[244:245], v[12:13], v[230:231]
	v_pk_mul_f32 v[246:247], v[14:15], v[234:235]
	v_pk_mul_f32 v[248:249], v[8:9], v[238:239]
	v_pk_mul_f32 v[250:251], v[10:11], v[240:241]
	v_lshlrev_b32_e32 v230, 16, v198
	v_and_b32_e32 v231, 0xffff0000, v198
	v_lshlrev_b32_e32 v234, 16, v199
	v_and_b32_e32 v235, 0xffff0000, v199
	v_lshlrev_b32_e32 v238, 16, v200
	v_and_b32_e32 v239, 0xffff0000, v200
	v_lshlrev_b32_e32 v240, 16, v201
	v_and_b32_e32 v241, 0xffff0000, v201
	v_pk_add_f32 v[244:245], v[244:245], v[230:231]
	v_pk_add_f32 v[246:247], v[246:247], v[234:235]
	v_pk_add_f32 v[248:249], v[248:249], v[238:239]
	v_pk_add_f32 v[250:251], v[250:251], v[240:241]
	v_cvt_pk_bf16_f32 v244, v244, v245
	v_cvt_pk_bf16_f32 v245, v246, v247
	v_cvt_pk_bf16_f32 v246, v248, v249
	v_cvt_pk_bf16_f32 v247, v250, v251
	global_store_dwordx4 v211, v[244:247], s[0:1] offset:256
	s_add_u32 s0, s0, 0x8000
	s_addc_u32 s1, s1, 0
	v_lshlrev_b32_e32 v230, 16, v186
	v_and_b32_e32 v231, 0xffff0000, v186
	v_lshlrev_b32_e32 v234, 16, v187
	v_and_b32_e32 v235, 0xffff0000, v187
	v_lshlrev_b32_e32 v238, 16, v188
	v_and_b32_e32 v239, 0xffff0000, v188
	v_lshlrev_b32_e32 v240, 16, v189
	v_and_b32_e32 v241, 0xffff0000, v189
	v_pk_mul_f32 v[244:245], v[68:69], v[230:231]
	v_pk_mul_f32 v[246:247], v[70:71], v[234:235]
	v_pk_mul_f32 v[248:249], v[64:65], v[238:239]
	v_pk_mul_f32 v[250:251], v[66:67], v[240:241]
	v_lshlrev_b32_e32 v230, 16, v202
	v_and_b32_e32 v231, 0xffff0000, v202
	v_lshlrev_b32_e32 v234, 16, v203
	v_and_b32_e32 v235, 0xffff0000, v203
	v_lshlrev_b32_e32 v238, 16, v204
	v_and_b32_e32 v239, 0xffff0000, v204
	v_lshlrev_b32_e32 v240, 16, v205
	v_and_b32_e32 v241, 0xffff0000, v205
	v_pk_add_f32 v[244:245], v[244:245], v[230:231]
	v_pk_add_f32 v[246:247], v[246:247], v[234:235]
	v_pk_add_f32 v[248:249], v[248:249], v[238:239]
	v_pk_add_f32 v[250:251], v[250:251], v[240:241]
	v_cvt_pk_bf16_f32 v244, v244, v245
	v_cvt_pk_bf16_f32 v245, v246, v247
	v_cvt_pk_bf16_f32 v246, v248, v249
	v_cvt_pk_bf16_f32 v247, v250, v251
	global_store_dwordx4 v211, v[244:247], s[0:1]
	v_lshlrev_b32_e32 v230, 16, v190
	v_and_b32_e32 v231, 0xffff0000, v190
	v_lshlrev_b32_e32 v234, 16, v191
	v_and_b32_e32 v235, 0xffff0000, v191
	v_lshlrev_b32_e32 v238, 16, v192
	v_and_b32_e32 v239, 0xffff0000, v192
	v_lshlrev_b32_e32 v240, 16, v193
	v_and_b32_e32 v241, 0xffff0000, v193
	v_pk_mul_f32 v[244:245], v[4:5], v[230:231]
	v_pk_mul_f32 v[246:247], v[6:7], v[234:235]
	v_pk_mul_f32 v[248:249], v[0:1], v[238:239]
	v_pk_mul_f32 v[250:251], v[2:3], v[240:241]
	v_lshlrev_b32_e32 v230, 16, v206
	v_and_b32_e32 v231, 0xffff0000, v206
	v_lshlrev_b32_e32 v234, 16, v207
	v_and_b32_e32 v235, 0xffff0000, v207
	v_lshlrev_b32_e32 v238, 16, v208
	v_and_b32_e32 v239, 0xffff0000, v208
	v_lshlrev_b32_e32 v240, 16, v209
	v_and_b32_e32 v241, 0xffff0000, v209
	v_pk_add_f32 v[244:245], v[244:245], v[230:231]
	v_pk_add_f32 v[246:247], v[246:247], v[234:235]
	v_pk_add_f32 v[248:249], v[248:249], v[238:239]
	v_pk_add_f32 v[250:251], v[250:251], v[240:241]
	v_cvt_pk_bf16_f32 v244, v244, v245
	v_cvt_pk_bf16_f32 v245, v246, v247
	v_cvt_pk_bf16_f32 v246, v248, v249
	v_cvt_pk_bf16_f32 v247, v250, v251
	global_store_dwordx4 v211, v[244:247], s[0:1] offset:256
	s_branch .LBB0_150
; __device__ __forceinline__ unsigned pk2(float lo, float hi) { const f32x2_t f = {lo, hi}; const bf16x2_t b = __builtin_convertvector(f, bf16x2_t); return __builtin_bit_cast(unsigned, b); }
; __device__ __forceinline__ float lo16(unsigned v) { return __uint_as_float(v << 16); }
; __device__ __forceinline__ float hi16(unsigned v) { return __uint_as_float(v & 0xffff0000u); }
;   __device__ __forceinline__ void operator()(const f32x4 (&acc)[2][2][4][2], const pg8::Unit& u, int wr, int wc, int fr, int fq) const {
;     ...
;     } else if (mode == EM_AB || mode == EM_HBR) {
;       const u16* sg = (const u16*)(ws + O_SG + (size_t)(slice & 1) * SG_BYTES) + (mode == EM_HBR ? 1024 : 0); u16* mg = (u16*)(ws + O_MG) + (size_t)slice * TS * 1024;
; #pragma unroll
;       for (int g8 = 0; g8 < 4; ++g8) {
;         const int ai = g8 >> 1, m0 = (g8 & 1) * 2;
;         u32x4 sv[2][2], pv[2][2];
; #pragma unroll
;         for (int mm = 0; mm < 2; ++mm)
; #pragma unroll
;           for (int bj = 0; bj < 2; ++bj) {
;             const int row = row0 + ai * 128 + (m0 + mm) * 16, c = col0 + bj * 128;
;             sv[mm][bj] = *(const u32x4*)(sg + (size_t)row * 2048 + c);
;             if (mode == EM_HBR) pv[mm][bj] = *(const u32x4*)(mg + (size_t)row * 1024 + c);
;           }
;         __builtin_amdgcn_sched_barrier(0);
; #pragma unroll
;         for (int mm = 0; mm < 2; ++mm)
; #pragma unroll
;           for (int bj = 0; bj < 2; ++bj) {
;             const int m = m0 + mm, row = row0 + ai * 128 + m * 16, c = col0 + bj * 128;
;             const u32x4 sx = sv[mm][bj];
;             const f32x4 a = acc[ai][bj][m][0], b = acc[ai][bj][m][1];
;             float v[8] = {a[0] * lo16(sx.x), a[1] * hi16(sx.x), a[2] * lo16(sx.y), a[3] * hi16(sx.y), b[0] * lo16(sx.z), b[1] * hi16(sx.z), b[2] * lo16(sx.w), b[3] * hi16(sx.w)};
;             if (mode == EM_HBR) { const u32x4 p = pv[mm][bj];
;               v[0] += lo16(p.x); v[1] += hi16(p.x); v[2] += lo16(p.y); v[3] += hi16(p.y); v[4] += lo16(p.z); v[5] += hi16(p.z); v[6] += lo16(p.w); v[7] += hi16(p.w); }
;             u32x4 o; o.x = pk2(v[0], v[1]); o.y = pk2(v[2], v[3]); o.z = pk2(v[4], v[5]); o.w = pk2(v[6], v[7]);
;             *(u32x4*)(mg + (size_t)row * 1024 + c) = o;
;           }
;         __builtin_amdgcn_sched_barrier(0);
;       }
.Labh_ab:
	global_load_dwordx4 v[130:133], v210, s[12:13]
	global_load_dwordx4 v[134:137], v210, s[12:13] offset:256
	s_add_u32 s12, s12, 0x10000
	s_addc_u32 s13, s13, 0
	global_load_dwordx4 v[138:141], v210, s[12:13]
	global_load_dwordx4 v[142:145], v210, s[12:13] offset:256
	s_add_u32 s12, s12, 0x10000
	s_addc_u32 s13, s13, 0
	global_load_dwordx4 v[178:181], v210, s[12:13]
	global_load_dwordx4 v[182:185], v210, s[12:13] offset:256
	s_add_u32 s12, s12, 0x10000
	s_addc_u32 s13, s13, 0
	global_load_dwordx4 v[186:189], v210, s[12:13]
	global_load_dwordx4 v[190:193], v210, s[12:13] offset:256
	s_add_u32 s12, s12, 0x50000
	s_addc_u32 s13, s13, 0
	s_waitcnt vmcnt(4)
	v_lshlrev_b32_e32 v230, 16, v130
	v_and_b32_e32 v231, 0xffff0000, v130
	v_lshlrev_b32_e32 v234, 16, v131
	v_and_b32_e32 v235, 0xffff0000, v131
	v_lshlrev_b32_e32 v238, 16, v132
	v_and_b32_e32 v239, 0xffff0000, v132
	v_lshlrev_b32_e32 v240, 16, v133
	v_and_b32_e32 v241, 0xffff0000, v133
	v_pk_mul_f32 v[244:245], v[126:127], v[230:231]
	v_pk_mul_f32 v[246:247], v[128:129], v[234:235]
	v_pk_mul_f32 v[248:249], v[122:123], v[238:239]
	v_pk_mul_f32 v[250:251], v[124:125], v[240:241]
	v_cvt_pk_bf16_f32 v244, v244, v245
	v_cvt_pk_bf16_f32 v245, v246, v247
	v_cvt_pk_bf16_f32 v246, v248, v249
	v_cvt_pk_bf16_f32 v247, v250, v251
	global_store_dwordx4 v211, v[244:247], s[0:1]
	v_lshlrev_b32_e32 v230, 16, v134
	v_and_b32_e32 v231, 0xffff0000, v134
	v_lshlrev_b32_e32 v234, 16, v135
	v_and_b32_e32 v235, 0xffff0000, v135
	v_lshlrev_b32_e32 v238, 16, v136
	v_and_b32_e32 v239, 0xffff0000, v136
	v_lshlrev_b32_e32 v240, 16, v137
	v_and_b32_e32 v241, 0xffff0000, v137
	v_pk_mul_f32 v[244:245], v[60:61], v[230:231]
	v_pk_mul_f32 v[246:247], v[62:63], v[234:235]
	v_pk_mul_f32 v[248:249], v[56:57], v[238:239]
	v_pk_mul_f32 v[250:251], v[58:59], v[240:241]
	v_cvt_pk_bf16_f32 v244, v244, v245
	v_cvt_pk_bf16_f32 v245, v246, v247
	v_cvt_pk_bf16_f32 v246, v248, v249
	v_cvt_pk_bf16_f32 v247, v250, v251
	global_store_dwordx4 v211, v[244:247], s[0:1] offset:256
	s_add_u32 s0, s0, 0x8000
	s_addc_u32 s1, s1, 0
	v_lshlrev_b32_e32 v230, 16, v138
	v_and_b32_e32 v231, 0xffff0000, v138
	v_lshlrev_b32_e32 v234, 16, v139
	v_and_b32_e32 v235, 0xffff0000, v139
	v_lshlrev_b32_e32 v238, 16, v140
	v_and_b32_e32 v239, 0xffff0000, v140
	v_lshlrev_b32_e32 v240, 16, v141
	v_and_b32_e32 v241, 0xffff0000, v141
	v_pk_mul_f32 v[244:245], v[118:119], v[230:231]
	v_pk_mul_f32 v[246:247], v[120:121], v[234:235]
	v_pk_mul_f32 v[248:249], v[114:115], v[238:239]
	v_pk_mul_f32 v[250:251], v[116:117], v[240:241]
	v_cvt_pk_bf16_f32 v244, v244, v245
	v_cvt_pk_bf16_f32 v245, v246, v247
	v_cvt_pk_bf16_f32 v246, v248, v249
	v_cvt_pk_bf16_f32 v247, v250, v251
	global_store_dwordx4 v211, v[244:247], s[0:1]
	v_lshlrev_b32_e32 v230, 16, v142
	v_and_b32_e32 v231, 0xffff0000, v142
	v_lshlrev_b32_e32 v234, 16, v143
	v_and_b32_e32 v235, 0xffff0000, v143
	v_lshlrev_b32_e32 v238, 16, v144
	v_and_b32_e32 v239, 0xffff0000, v144
	v_lshlrev_b32_e32 v240, 16, v145
	v_and_b32_e32 v241, 0xffff0000, v145
	v_pk_mul_f32 v[244:245], v[52:53], v[230:231]
	v_pk_mul_f32 v[246:247], v[54:55], v[234:235]
	v_pk_mul_f32 v[248:249], v[48:49], v[238:239]
	v_pk_mul_f32 v[250:251], v[50:51], v[240:241]
	v_cvt_pk_bf16_f32 v244, v244, v245
	v_cvt_pk_bf16_f32 v245, v246, v247
	v_cvt_pk_bf16_f32 v246, v248, v249
	v_cvt_pk_bf16_f32 v247, v250, v251
	global_store_dwordx4 v211, v[244:247], s[0:1] offset:256
	s_add_u32 s0, s0, 0x8000
	s_addc_u32 s1, s1, 0
	global_load_dwordx4 v[130:133], v210, s[12:13]
	global_load_dwordx4 v[134:137], v210, s[12:13] offset:256
	s_add_u32 s12, s12, 0x10000
	s_addc_u32 s13, s13, 0
	global_load_dwordx4 v[138:141], v210, s[12:13]
	global_load_dwordx4 v[142:145], v210, s[12:13] offset:256
	s_add_u32 s12, s12, 0x10000
	s_addc_u32 s13, s13, 0
	s_waitcnt vmcnt(8)
	v_lshlrev_b32_e32 v230, 16, v178
	v_and_b32_e32 v231, 0xffff0000, v178
	v_lshlrev_b32_e32 v234, 16, v179
	v_and_b32_e32 v235, 0xffff0000, v179
	v_lshlrev_b32_e32 v238, 16, v180
	v_and_b32_e32 v239, 0xffff0000, v180
	v_lshlrev_b32_e32 v240, 16, v181
	v_and_b32_e32 v241, 0xffff0000, v181
	v_pk_mul_f32 v[244:245], v[110:111], v[230:231]
	v_pk_mul_f32 v[246:247], v[112:113], v[234:235]
	v_pk_mul_f32 v[248:249], v[106:107], v[238:239]
	v_pk_mul_f32 v[250:251], v[108:109], v[240:241]
	v_cvt_pk_bf16_f32 v244, v244, v245
	v_cvt_pk_bf16_f32 v245, v246, v247
	v_cvt_pk_bf16_f32 v246, v248, v249
	v_cvt_pk_bf16_f32 v247, v250, v251
	global_store_dwordx4 v211, v[244:247], s[0:1]
	v_lshlrev_b32_e32 v230, 16, v182
	v_and_b32_e32 v231, 0xffff0000, v182
	v_lshlrev_b32_e32 v234, 16, v183
	v_and_b32_e32 v235, 0xffff0000, v183
	v_lshlrev_b32_e32 v238, 16, v184
	v_and_b32_e32 v239, 0xffff0000, v184
	v_lshlrev_b32_e32 v240, 16, v185
	v_and_b32_e32 v241, 0xffff0000, v185
	v_pk_mul_f32 v[244:245], v[44:45], v[230:231]
	v_pk_mul_f32 v[246:247], v[46:47], v[234:235]
	v_pk_mul_f32 v[248:249], v[40:41], v[238:239]
	v_pk_mul_f32 v[250:251], v[42:43], v[240:241]
	v_cvt_pk_bf16_f32 v244, v244, v245
	v_cvt_pk_bf16_f32 v245, v246, v247
	v_cvt_pk_bf16_f32 v246, v248, v249
	v_cvt_pk_bf16_f32 v247, v250, v251
	global_store_dwordx4 v211, v[244:247], s[0:1] offset:256
	s_add_u32 s0, s0, 0x8000
	s_addc_u32 s1, s1, 0
	v_lshlrev_b32_e32 v230, 16, v186
	v_and_b32_e32 v231, 0xffff0000, v186
	v_lshlrev_b32_e32 v234, 16, v187
	v_and_b32_e32 v235, 0xffff0000, v187
	v_lshlrev_b32_e32 v238, 16, v188
	v_and_b32_e32 v239, 0xffff0000, v188
	v_lshlrev_b32_e32 v240, 16, v189
	v_and_b32_e32 v241, 0xffff0000, v189
	v_pk_mul_f32 v[244:245], v[102:103], v[230:231]
	v_pk_mul_f32 v[246:247], v[104:105], v[234:235]
	v_pk_mul_f32 v[248:249], v[98:99], v[238:239]
	v_pk_mul_f32 v[250:251], v[100:101], v[240:241]
	v_cvt_pk_bf16_f32 v244, v244, v245
	v_cvt_pk_bf16_f32 v245, v246, v247
	v_cvt_pk_bf16_f32 v246, v248, v249
	v_cvt_pk_bf16_f32 v247, v250, v251
	global_store_dwordx4 v211, v[244:247], s[0:1]
	v_lshlrev_b32_e32 v230, 16, v190
	v_and_b32_e32 v231, 0xffff0000, v190
	v_lshlrev_b32_e32 v234, 16, v191
	v_and_b32_e32 v235, 0xffff0000, v191
	v_lshlrev_b32_e32 v238, 16, v192
	v_and_b32_e32 v239, 0xffff0000, v192
	v_lshlrev_b32_e32 v240, 16, v193
	v_and_b32_e32 v241, 0xffff0000, v193
	v_pk_mul_f32 v[244:245], v[36:37], v[230:231]
	v_pk_mul_f32 v[246:247], v[38:39], v[234:235]
	v_pk_mul_f32 v[248:249], v[32:33], v[238:239]
	v_pk_mul_f32 v[250:251], v[34:35], v[240:241]
	v_cvt_pk_bf16_f32 v244, v244, v245
	v_cvt_pk_bf16_f32 v245, v246, v247
	v_cvt_pk_bf16_f32 v246, v248, v249
	v_cvt_pk_bf16_f32 v247, v250, v251
	global_store_dwordx4 v211, v[244:247], s[0:1] offset:256
	s_add_u32 s0, s0, 0x28000
	s_addc_u32 s1, s1, 0
	global_load_dwordx4 v[178:181], v210, s[12:13]
	global_load_dwordx4 v[182:185], v210, s[12:13] offset:256
	s_add_u32 s12, s12, 0x10000
	s_addc_u32 s13, s13, 0
	global_load_dwordx4 v[186:189], v210, s[12:13]
	global_load_dwordx4 v[190:193], v210, s[12:13] offset:256
	s_waitcnt vmcnt(8)
; __device__ __forceinline__ unsigned pk2(float lo, float hi) { const f32x2_t f = {lo, hi}; const bf16x2_t b = __builtin_convertvector(f, bf16x2_t); return __builtin_bit_cast(unsigned, b); }
; __device__ __forceinline__ float lo16(unsigned v) { return __uint_as_float(v << 16); }
; __device__ __forceinline__ float hi16(unsigned v) { return __uint_as_float(v & 0xffff0000u); }
;   __device__ __forceinline__ void operator()(const f32x4 (&acc)[2][2][4][2], const pg8::Unit& u, int wr, int wc, int fr, int fq) const {
;     ...
;     } else if (mode == EM_AB || mode == EM_HBR) {
;       const u16* sg = (const u16*)(ws + O_SG + (size_t)(slice & 1) * SG_BYTES) + (mode == EM_HBR ? 1024 : 0); u16* mg = (u16*)(ws + O_MG) + (size_t)slice * TS * 1024;
; #pragma unroll
;       for (int g8 = 0; g8 < 4; ++g8) {
;         const int ai = g8 >> 1, m0 = (g8 & 1) * 2;
;         u32x4 sv[2][2], pv[2][2];
; #pragma unroll
;         for (int mm = 0; mm < 2; ++mm)
; #pragma unroll
;           for (int bj = 0; bj < 2; ++bj) {
;             const int row = row0 + ai * 128 + (m0 + mm) * 16, c = col0 + bj * 128;
;             sv[mm][bj] = *(const u32x4*)(sg + (size_t)row * 2048 + c);
;             if (mode == EM_HBR) pv[mm][bj] = *(const u32x4*)(mg + (size_t)row * 1024 + c);
;           }
;         __builtin_amdgcn_sched_barrier(0);
; #pragma unroll
;         for (int mm = 0; mm < 2; ++mm)
; #pragma unroll
;           for (int bj = 0; bj < 2; ++bj) {
;             const int m = m0 + mm, row = row0 + ai * 128 + m * 16, c = col0 + bj * 128;
;             const u32x4 sx = sv[mm][bj];
;             const f32x4 a = acc[ai][bj][m][0], b = acc[ai][bj][m][1];
;             float v[8] = {a[0] * lo16(sx.x), a[1] * hi16(sx.x), a[2] * lo16(sx.y), a[3] * hi16(sx.y), b[0] * lo16(sx.z), b[1] * hi16(sx.z), b[2] * lo16(sx.w), b[3] * hi16(sx.w)};
;             if (mode == EM_HBR) { const u32x4 p = pv[mm][bj];
;               v[0] += lo16(p.x); v[1] += hi16(p.x); v[2] += lo16(p.y); v[3] += hi16(p.y); v[4] += lo16(p.z); v[5] += hi16(p.z); v[6] += lo16(p.w); v[7] += hi16(p.w); }
;             u32x4 o; o.x = pk2(v[0], v[1]); o.y = pk2(v[2], v[3]); o.z = pk2(v[4], v[5]); o.w = pk2(v[6], v[7]);
;             *(u32x4*)(mg + (size_t)row * 1024 + c) = o;
;           }
;         __builtin_amdgcn_sched_barrier(0);
;       }
	v_lshlrev_b32_e32 v230, 16, v130
	v_and_b32_e32 v231, 0xffff0000, v130
	v_lshlrev_b32_e32 v234, 16, v131
	v_and_b32_e32 v235, 0xffff0000, v131
	v_lshlrev_b32_e32 v238, 16, v132
	v_and_b32_e32 v239, 0xffff0000, v132
	v_lshlrev_b32_e32 v240, 16, v133
	v_and_b32_e32 v241, 0xffff0000, v133
	v_pk_mul_f32 v[244:245], v[94:95], v[230:231]
	v_pk_mul_f32 v[246:247], v[96:97], v[234:235]
	v_pk_mul_f32 v[248:249], v[90:91], v[238:239]
	v_pk_mul_f32 v[250:251], v[92:93], v[240:241]
	v_cvt_pk_bf16_f32 v244, v244, v245
	v_cvt_pk_bf16_f32 v245, v246, v247
	v_cvt_pk_bf16_f32 v246, v248, v249
	v_cvt_pk_bf16_f32 v247, v250, v251
	global_store_dwordx4 v211, v[244:247], s[0:1]
	v_lshlrev_b32_e32 v230, 16, v134
	v_and_b32_e32 v231, 0xffff0000, v134
	v_lshlrev_b32_e32 v234, 16, v135
	v_and_b32_e32 v235, 0xffff0000, v135
	v_lshlrev_b32_e32 v238, 16, v136
	v_and_b32_e32 v239, 0xffff0000, v136
	v_lshlrev_b32_e32 v240, 16, v137
	v_and_b32_e32 v241, 0xffff0000, v137
	v_pk_mul_f32 v[244:245], v[28:29], v[230:231]
	v_pk_mul_f32 v[246:247], v[30:31], v[234:235]
	v_pk_mul_f32 v[248:249], v[24:25], v[238:239]
	v_pk_mul_f32 v[250:251], v[26:27], v[240:241]
	v_cvt_pk_bf16_f32 v244, v244, v245
	v_cvt_pk_bf16_f32 v245, v246, v247
	v_cvt_pk_bf16_f32 v246, v248, v249
	v_cvt_pk_bf16_f32 v247, v250, v251
	global_store_dwordx4 v211, v[244:247], s[0:1] offset:256
	s_add_u32 s0, s0, 0x8000
	s_addc_u32 s1, s1, 0
	v_lshlrev_b32_e32 v230, 16, v138
	v_and_b32_e32 v231, 0xffff0000, v138
	v_lshlrev_b32_e32 v234, 16, v139
	v_and_b32_e32 v235, 0xffff0000, v139
	v_lshlrev_b32_e32 v238, 16, v140
	v_and_b32_e32 v239, 0xffff0000, v140
	v_lshlrev_b32_e32 v240, 16, v141
	v_and_b32_e32 v241, 0xffff0000, v141
	v_pk_mul_f32 v[244:245], v[86:87], v[230:231]
	v_pk_mul_f32 v[246:247], v[88:89], v[234:235]
	v_pk_mul_f32 v[248:249], v[82:83], v[238:239]
	v_pk_mul_f32 v[250:251], v[84:85], v[240:241]
	v_cvt_pk_bf16_f32 v244, v244, v245
	v_cvt_pk_bf16_f32 v245, v246, v247
	v_cvt_pk_bf16_f32 v246, v248, v249
	v_cvt_pk_bf16_f32 v247, v250, v251
	global_store_dwordx4 v211, v[244:247], s[0:1]
	v_lshlrev_b32_e32 v230, 16, v142
	v_and_b32_e32 v231, 0xffff0000, v142
	v_lshlrev_b32_e32 v234, 16, v143
	v_and_b32_e32 v235, 0xffff0000, v143
	v_lshlrev_b32_e32 v238, 16, v144
	v_and_b32_e32 v239, 0xffff0000, v144
	v_lshlrev_b32_e32 v240, 16, v145
	v_and_b32_e32 v241, 0xffff0000, v145
	v_pk_mul_f32 v[244:245], v[20:21], v[230:231]
	v_pk_mul_f32 v[246:247], v[22:23], v[234:235]
	v_pk_mul_f32 v[248:249], v[16:17], v[238:239]
	v_pk_mul_f32 v[250:251], v[18:19], v[240:241]
	v_cvt_pk_bf16_f32 v244, v244, v245
	v_cvt_pk_bf16_f32 v245, v246, v247
	v_cvt_pk_bf16_f32 v246, v248, v249
	v_cvt_pk_bf16_f32 v247, v250, v251
	global_store_dwordx4 v211, v[244:247], s[0:1] offset:256
	s_add_u32 s0, s0, 0x8000
	s_addc_u32 s1, s1, 0
	s_waitcnt vmcnt(4)
	v_lshlrev_b32_e32 v230, 16, v178
	v_and_b32_e32 v231, 0xffff0000, v178
	v_lshlrev_b32_e32 v234, 16, v179
	v_and_b32_e32 v235, 0xffff0000, v179
	v_lshlrev_b32_e32 v238, 16, v180
	v_and_b32_e32 v239, 0xffff0000, v180
	v_lshlrev_b32_e32 v240, 16, v181
	v_and_b32_e32 v241, 0xffff0000, v181
	v_pk_mul_f32 v[244:245], v[76:77], v[230:231]
	v_pk_mul_f32 v[246:247], v[78:79], v[234:235]
	v_pk_mul_f32 v[248:249], v[72:73], v[238:239]
	v_pk_mul_f32 v[250:251], v[74:75], v[240:241]
	v_cvt_pk_bf16_f32 v244, v244, v245
	v_cvt_pk_bf16_f32 v245, v246, v247
	v_cvt_pk_bf16_f32 v246, v248, v249
	v_cvt_pk_bf16_f32 v247, v250, v251
	global_store_dwordx4 v211, v[244:247], s[0:1]
	v_lshlrev_b32_e32 v230, 16, v182
	v_and_b32_e32 v231, 0xffff0000, v182
	v_lshlrev_b32_e32 v234, 16, v183
	v_and_b32_e32 v235, 0xffff0000, v183
	v_lshlrev_b32_e32 v238, 16, v184
	v_and_b32_e32 v239, 0xffff0000, v184
	v_lshlrev_b32_e32 v240, 16, v185
	v_and_b32_e32 v241, 0xffff0000, v185
	v_pk_mul_f32 v[244:245], v[12:13], v[230:231]
	v_pk_mul_f32 v[246:247], v[14:15], v[234:235]
	v_pk_mul_f32 v[248:249], v[8:9], v[238:239]
	v_pk_mul_f32 v[250:251], v[10:11], v[240:241]
	v_cvt_pk_bf16_f32 v244, v244, v245
	v_cvt_pk_bf16_f32 v245, v246, v247
	v_cvt_pk_bf16_f32 v246, v248, v249
	v_cvt_pk_bf16_f32 v247, v250, v251
	global_store_dwordx4 v211, v[244:247], s[0:1] offset:256
	s_add_u32 s0, s0, 0x8000
	s_addc_u32 s1, s1, 0
	v_lshlrev_b32_e32 v230, 16, v186
	v_and_b32_e32 v231, 0xffff0000, v186
	v_lshlrev_b32_e32 v234, 16, v187
	v_and_b32_e32 v235, 0xffff0000, v187
	v_lshlrev_b32_e32 v238, 16, v188
	v_and_b32_e32 v239, 0xffff0000, v188
	v_lshlrev_b32_e32 v240, 16, v189
	v_and_b32_e32 v241, 0xffff0000, v189
	v_pk_mul_f32 v[244:245], v[68:69], v[230:231]
	v_pk_mul_f32 v[246:247], v[70:71], v[234:235]
	v_pk_mul_f32 v[248:249], v[64:65], v[238:239]
	v_pk_mul_f32 v[250:251], v[66:67], v[240:241]
	v_cvt_pk_bf16_f32 v244, v244, v245
	v_cvt_pk_bf16_f32 v245, v246, v247
	v_cvt_pk_bf16_f32 v246, v248, v249
	v_cvt_pk_bf16_f32 v247, v250, v251
	global_store_dwordx4 v211, v[244:247], s[0:1]
	v_lshlrev_b32_e32 v230, 16, v190
	v_and_b32_e32 v231, 0xffff0000, v190
	v_lshlrev_b32_e32 v234, 16, v191
	v_and_b32_e32 v235, 0xffff0000, v191
	v_lshlrev_b32_e32 v238, 16, v192
	v_and_b32_e32 v239, 0xffff0000, v192
	v_lshlrev_b32_e32 v240, 16, v193
	v_and_b32_e32 v241, 0xffff0000, v193
	v_pk_mul_f32 v[244:245], v[4:5], v[230:231]
	v_pk_mul_f32 v[246:247], v[6:7], v[234:235]
	v_pk_mul_f32 v[248:249], v[0:1], v[238:239]
	v_pk_mul_f32 v[250:251], v[2:3], v[240:241]
	v_cvt_pk_bf16_f32 v244, v244, v245
	v_cvt_pk_bf16_f32 v245, v246, v247
	v_cvt_pk_bf16_f32 v246, v248, v249
	v_cvt_pk_bf16_f32 v247, v250, v251
	global_store_dwordx4 v211, v[244:247], s[0:1] offset:256
	s_branch .LBB0_150
	v_ashrrev_i32_e32 v177, 31, v176
	v_lshlrev_b64 v[130:131], 12, v[176:177]
	v_lshl_add_u64 v[130:131], s[60:61], 0, v[130:131]
	v_ashrrev_i32_e32 v175, 31, v174
	v_lshl_add_u64 v[130:131], v[174:175], 1, v[130:131]
	flat_load_dwordx4 v[158:161], v[130:131]
	v_readlane_b32 s12, v254, 39
	v_lshlrev_b64 v[132:133], 11, v[176:177]
	v_readlane_b32 s13, v254, 40
	v_lshl_add_u64 v[132:133], s[4:5], 0, v[132:133]
	s_andn2_b64 vcc, exec, s[12:13]
	s_waitcnt lgkmcnt(0)
	v_cndmask_b32_e64 v80, 0, 1, s[12:13]
	v_cmp_ne_u32_e64 s[10:11], 1, v80
	v_lshl_add_u64 v[180:181], v[174:175], 1, v[132:133]
	s_cbranch_vccnz .LBB0_87
	flat_load_dwordx4 v[142:145], v[180:181]
